# v26 + nt hint on the P1-tail bf16 weight-copy stores (first needed in P4+)
# baseline (speedup 1.0000x reference)
; #define GAS __attribute__((address_space(1)))
; #define LAS __attribute__((address_space(3)))
; __device__ __forceinline__ void transpose_item(const float* W, int ldw, bf16* WT, int K, int k0, int sn0, int dn0, int lane, LAS unsigned char* T, const float* kgain = nullptr) {
;     ...
; #pragma unroll
;     for (int i = 0; i < 8; ++i) { const int n = 8 * i + (lane >> 3), p = lane & 7, s = (n >> 2) & 15;
;         v4u o = *(const LAS v4u*)(T + n * 128 + ((p ^ (s >> 1)) << 4));
;         if (s & 1) { const unsigned tx = o.x, ty = o.y; o.x = o.z; o.y = o.w; o.z = tx; o.w = ty; }
;         *(GAS v4u*)(WT + (size_t)(dn0 + n) * K + k0 + 8 * p) = o; }
; template <int PART> __device__ __forceinline__ void deferred_transposes(Frame& F, int gw, int ngw) {
;     bf16* WgluT = (bf16*)(F.ws + WS_WGLU); bf16* WoutT = (bf16*)(F.ws + WS_WOUT); bf16* WguT = (bf16*)(F.ws + WS_WGU); bf16* WdT = (bf16*)(F.ws + WS_WD);
;     constexpr int I_GLU = (S5W / 64) * (S5W / 64), I_OUT = (DM / 64) * (DM / 64), I_G = (DM / 64) * (DFF / 64), I_D = (DFF / 64) * (DM / 64);
;     constexpr int N0 = I_GLU + I_OUT + 2 * I_G, NITEMS = (PART == 0) ? N0 : I_D;
;     for (int it = gw; it < NITEMS; it += ngw) {
;         int r = (PART == 0) ? it : it + N0;
;         if (r < I_GLU) { const int nblk = S5W / 64, kb = r / nblk, nb = r % nblk; transpose_item(F.in[16], S5W, WgluT, S5W, kb * 64, nb * 64, nb * 64, F.lane, F.lds + F.wave * 8192); continue; } r -= I_GLU;
;         if (r < I_OUT) { const int nblk = DM / 64, kb = r / nblk, nb = r % nblk; transpose_item(F.in[18], DM, WoutT, DM, kb * 64, nb * 64, nb * 64, F.lane, F.lds + F.wave * 8192); continue; } r -= I_OUT;
;         if (r < I_G) { const int nblk = DFF / 64, kb = r / nblk, nb = r % nblk, sn0 = nb * 64; transpose_item(F.in[20], DFF, WguT, DM, kb * 64, sn0, 256 * (sn0 / 128) + (sn0 % 128), F.lane, F.lds + F.wave * 8192, F.in[19]); continue; } r -= I_G;
;         if (r < I_G) { const int nblk = DFF / 64, kb = r / nblk, nb = r % nblk, sn0 = nb * 64; transpose_item(F.in[21], DFF, WguT, DM, kb * 64, sn0, 256 * (sn0 / 128) + 128 + (sn0 % 128), F.lane, F.lds + F.wave * 8192, F.in[19]); continue; } r -= I_G;
;         { const int nblk = DM / 64, kb = r / nblk, nb = r % nblk; transpose_item(F.in[22], DM, WdT, DFF, kb * 64, nb * 64, nb * 64, F.lane, F.lds + F.wave * 8192); }
;     }
.LBB0_156:
	ds_read_b128 v[4:7], v78
	ds_read_b128 v[8:11], v79
	s_add_i32 s3, s3, s14
	s_add_i32 s15, s15, s16
	s_add_i32 s17, s17, s18
	s_waitcnt lgkmcnt(0)
	v_cndmask_b32_e64 v14, v4, v6, s[0:1]
	v_cndmask_b32_e64 v12, v6, v4, s[0:1]
	v_or_b32_e32 v4, s10, v70
	v_cndmask_b32_e64 v15, v5, v7, s[0:1]
	v_cndmask_b32_e64 v13, v7, v5, s[0:1]
	v_ashrrev_i32_e32 v5, 31, v4
	v_lshlrev_b64 v[4:5], s12, v[4:5]
	v_lshl_add_u64 v[4:5], v[2:3], 0, v[4:5]
	global_store_dwordx4 v[4:5], v[12:15], off nt
	v_cndmask_b32_e64 v7, v9, v11, s[0:1]
	v_cndmask_b32_e64 v6, v8, v10, s[0:1]
	v_cndmask_b32_e64 v5, v11, v9, s[0:1]
	v_cndmask_b32_e64 v4, v10, v8, s[0:1]
	v_add_u32_e32 v12, s10, v71
	ds_read_b128 v[8:11], v80
	v_ashrrev_i32_e32 v13, 31, v12
	v_lshlrev_b64 v[12:13], s12, v[12:13]
	v_lshl_add_u64 v[12:13], v[2:3], 0, v[12:13]
	global_store_dwordx4 v[12:13], v[4:7], off nt
	ds_read_b128 v[4:7], v81
	s_waitcnt lgkmcnt(0)
	v_cndmask_b32_e64 v12, v8, v10, s[0:1]
	v_cndmask_b32_e64 v10, v10, v8, s[0:1]
	v_add_u32_e32 v8, s10, v72
	v_cndmask_b32_e64 v13, v9, v11, s[0:1]
	v_cndmask_b32_e64 v11, v11, v9, s[0:1]
	v_ashrrev_i32_e32 v9, 31, v8
	v_lshlrev_b64 v[8:9], s12, v[8:9]
	v_lshl_add_u64 v[8:9], v[2:3], 0, v[8:9]
	global_store_dwordx4 v[8:9], v[10:13], off nt
	v_cndmask_b32_e64 v8, v4, v6, s[0:1]
	v_cndmask_b32_e64 v6, v6, v4, s[0:1]
	v_add_u32_e32 v4, s10, v73
	v_cndmask_b32_e64 v9, v5, v7, s[0:1]
	v_cndmask_b32_e64 v7, v7, v5, s[0:1]
	v_ashrrev_i32_e32 v5, 31, v4
	v_lshlrev_b64 v[4:5], s12, v[4:5]
	ds_read_b128 v[10:13], v82
	v_lshl_add_u64 v[4:5], v[2:3], 0, v[4:5]
	global_store_dwordx4 v[4:5], v[6:9], off nt
	ds_read_b128 v[4:7], v83
	s_cmpk_lt_i32 s3, 0x6c0
	v_add_u32_e32 v8, s10, v74
	v_ashrrev_i32_e32 v9, 31, v8
	v_lshlrev_b64 v[8:9], s12, v[8:9]
	s_waitcnt lgkmcnt(0)
	v_cndmask_b32_e64 v15, v11, v13, s[0:1]
	v_cndmask_b32_e64 v14, v10, v12, s[0:1]
	v_cndmask_b32_e64 v13, v13, v11, s[0:1]
	v_cndmask_b32_e64 v12, v12, v10, s[0:1]
	v_lshl_add_u64 v[8:9], v[2:3], 0, v[8:9]
	global_store_dwordx4 v[8:9], v[12:15], off nt
	v_cndmask_b32_e64 v8, v4, v6, s[0:1]
	v_cndmask_b32_e64 v6, v6, v4, s[0:1]
	v_add_u32_e32 v4, s10, v75
	v_cndmask_b32_e64 v9, v5, v7, s[0:1]
	v_cndmask_b32_e64 v7, v7, v5, s[0:1]
	v_ashrrev_i32_e32 v5, 31, v4
	v_lshlrev_b64 v[4:5], s12, v[4:5]
	ds_read_b128 v[10:13], v84
	v_lshl_add_u64 v[4:5], v[2:3], 0, v[4:5]
	global_store_dwordx4 v[4:5], v[6:9], off nt
	ds_read_b128 v[4:7], v85
	s_waitcnt lgkmcnt(0)
	v_cndmask_b32_e64 v15, v11, v13, s[0:1]
	v_add_u32_e32 v8, s10, v76
	v_ashrrev_i32_e32 v9, 31, v8
	v_lshlrev_b64 v[8:9], s12, v[8:9]
	v_cndmask_b32_e64 v14, v10, v12, s[0:1]
	v_cndmask_b32_e64 v13, v13, v11, s[0:1]
	v_cndmask_b32_e64 v12, v12, v10, s[0:1]
	v_lshl_add_u64 v[8:9], v[2:3], 0, v[8:9]
	global_store_dwordx4 v[8:9], v[12:15], off nt
	v_cndmask_b32_e64 v8, v4, v6, s[0:1]
	v_cndmask_b32_e64 v6, v6, v4, s[0:1]
	v_add_u32_e32 v4, s10, v77
	v_cndmask_b32_e64 v9, v5, v7, s[0:1]
	v_cndmask_b32_e64 v7, v7, v5, s[0:1]
	v_ashrrev_i32_e32 v5, 31, v4
	v_lshlrev_b64 v[4:5], s12, v[4:5]
	v_lshl_add_u64 v[2:3], v[2:3], 0, v[4:5]
	global_store_dwordx4 v[2:3], v[6:9], off nt
	s_cbranch_scc0 .LBB0_185

; #define GAS __attribute__((address_space(1)))
; #define LAS __attribute__((address_space(3)))
; __device__ __forceinline__ void transpose_item(const float* W, int ldw, bf16* WT, int K, int k0, int sn0, int dn0, int lane, LAS unsigned char* T, const float* kgain = nullptr) {
;     ...
; #pragma unroll
;     for (int i = 0; i < 8; ++i) { const int n = 8 * i + (lane >> 3), p = lane & 7, s = (n >> 2) & 15;
;         v4u o = *(const LAS v4u*)(T + n * 128 + ((p ^ (s >> 1)) << 4));
;         if (s & 1) { const unsigned tx = o.x, ty = o.y; o.x = o.z; o.y = o.w; o.z = tx; o.w = ty; }
;         *(GAS v4u*)(WT + (size_t)(dn0 + n) * K + k0 + 8 * p) = o; }
; template <int PART> __device__ __forceinline__ void deferred_transposes(Frame& F, int gw, int ngw) {
;     bf16* WgluT = (bf16*)(F.ws + WS_WGLU); bf16* WoutT = (bf16*)(F.ws + WS_WOUT); bf16* WguT = (bf16*)(F.ws + WS_WGU); bf16* WdT = (bf16*)(F.ws + WS_WD);
;     constexpr int I_GLU = (S5W / 64) * (S5W / 64), I_OUT = (DM / 64) * (DM / 64), I_G = (DM / 64) * (DFF / 64), I_D = (DFF / 64) * (DM / 64);
;     constexpr int N0 = I_GLU + I_OUT + 2 * I_G, NITEMS = (PART == 0) ? N0 : I_D;
;     for (int it = gw; it < NITEMS; it += ngw) {
;         int r = (PART == 0) ? it : it + N0;
;         if (r < I_GLU) { const int nblk = S5W / 64, kb = r / nblk, nb = r % nblk; transpose_item(F.in[16], S5W, WgluT, S5W, kb * 64, nb * 64, nb * 64, F.lane, F.lds + F.wave * 8192); continue; } r -= I_GLU;
;         if (r < I_OUT) { const int nblk = DM / 64, kb = r / nblk, nb = r % nblk; transpose_item(F.in[18], DM, WoutT, DM, kb * 64, nb * 64, nb * 64, F.lane, F.lds + F.wave * 8192); continue; } r -= I_OUT;
;         if (r < I_G) { const int nblk = DFF / 64, kb = r / nblk, nb = r % nblk, sn0 = nb * 64; transpose_item(F.in[20], DFF, WguT, DM, kb * 64, sn0, 256 * (sn0 / 128) + (sn0 % 128), F.lane, F.lds + F.wave * 8192, F.in[19]); continue; } r -= I_G;
;         if (r < I_G) { const int nblk = DFF / 64, kb = r / nblk, nb = r % nblk, sn0 = nb * 64; transpose_item(F.in[21], DFF, WguT, DM, kb * 64, sn0, 256 * (sn0 / 128) + 128 + (sn0 % 128), F.lane, F.lds + F.wave * 8192, F.in[19]); continue; } r -= I_G;
;         { const int nblk = DM / 64, kb = r / nblk, nb = r % nblk; transpose_item(F.in[22], DM, WdT, DFF, kb * 64, nb * 64, nb * 64, F.lane, F.lds + F.wave * 8192); }
;     }
.LBB0_189:
	ds_read_b128 v[4:7], v78
	ds_read_b128 v[8:11], v79
	s_add_i32 s18, s18, s19
	s_add_i32 s3, s3, s14
	s_add_i32 s15, s15, s16
	s_waitcnt lgkmcnt(0)
	v_cndmask_b32_e64 v14, v4, v6, s[0:1]
	v_cndmask_b32_e64 v12, v6, v4, s[0:1]
	v_or_b32_e32 v4, s10, v70
	v_cndmask_b32_e64 v15, v5, v7, s[0:1]
	v_cndmask_b32_e64 v13, v7, v5, s[0:1]
	v_ashrrev_i32_e32 v5, 31, v4
	v_lshlrev_b64 v[4:5], s12, v[4:5]
	v_lshl_add_u64 v[4:5], v[2:3], 0, v[4:5]
	global_store_dwordx4 v[4:5], v[12:15], off nt
	v_cndmask_b32_e64 v7, v9, v11, s[0:1]
	v_cndmask_b32_e64 v6, v8, v10, s[0:1]
	v_cndmask_b32_e64 v5, v11, v9, s[0:1]
	v_cndmask_b32_e64 v4, v10, v8, s[0:1]
	v_add_u32_e32 v12, s10, v71
	ds_read_b128 v[8:11], v80
	v_ashrrev_i32_e32 v13, 31, v12
	v_lshlrev_b64 v[12:13], s12, v[12:13]
	v_lshl_add_u64 v[12:13], v[2:3], 0, v[12:13]
	global_store_dwordx4 v[12:13], v[4:7], off nt
	ds_read_b128 v[4:7], v81
	s_waitcnt lgkmcnt(0)
	v_cndmask_b32_e64 v12, v8, v10, s[0:1]
	v_cndmask_b32_e64 v10, v10, v8, s[0:1]
	v_add_u32_e32 v8, s10, v72
	v_cndmask_b32_e64 v13, v9, v11, s[0:1]
	v_cndmask_b32_e64 v11, v11, v9, s[0:1]
	v_ashrrev_i32_e32 v9, 31, v8
	v_lshlrev_b64 v[8:9], s12, v[8:9]
	v_lshl_add_u64 v[8:9], v[2:3], 0, v[8:9]
	global_store_dwordx4 v[8:9], v[10:13], off nt
	v_cndmask_b32_e64 v8, v4, v6, s[0:1]
	v_cndmask_b32_e64 v6, v6, v4, s[0:1]
	v_add_u32_e32 v4, s10, v73
	v_cndmask_b32_e64 v9, v5, v7, s[0:1]
	v_cndmask_b32_e64 v7, v7, v5, s[0:1]
	v_ashrrev_i32_e32 v5, 31, v4
	v_lshlrev_b64 v[4:5], s12, v[4:5]
	ds_read_b128 v[10:13], v82
	v_lshl_add_u64 v[4:5], v[2:3], 0, v[4:5]
	global_store_dwordx4 v[4:5], v[6:9], off nt
	ds_read_b128 v[4:7], v83
	s_cmpk_gt_i32 s18, 0x6bf
	v_add_u32_e32 v8, s10, v74
	v_ashrrev_i32_e32 v9, 31, v8
	v_lshlrev_b64 v[8:9], s12, v[8:9]
	s_waitcnt lgkmcnt(0)
	v_cndmask_b32_e64 v15, v11, v13, s[0:1]
	v_cndmask_b32_e64 v14, v10, v12, s[0:1]
	v_cndmask_b32_e64 v13, v13, v11, s[0:1]
	v_cndmask_b32_e64 v12, v12, v10, s[0:1]
	v_lshl_add_u64 v[8:9], v[2:3], 0, v[8:9]
	global_store_dwordx4 v[8:9], v[12:15], off nt
	v_cndmask_b32_e64 v8, v4, v6, s[0:1]
	v_cndmask_b32_e64 v6, v6, v4, s[0:1]
	v_add_u32_e32 v4, s10, v75
	v_cndmask_b32_e64 v9, v5, v7, s[0:1]
	v_cndmask_b32_e64 v7, v7, v5, s[0:1]
	v_ashrrev_i32_e32 v5, 31, v4
	v_lshlrev_b64 v[4:5], s12, v[4:5]
	ds_read_b128 v[10:13], v84
	v_lshl_add_u64 v[4:5], v[2:3], 0, v[4:5]
	global_store_dwordx4 v[4:5], v[6:9], off nt
	ds_read_b128 v[4:7], v85
	s_waitcnt lgkmcnt(0)
	v_cndmask_b32_e64 v15, v11, v13, s[0:1]
	v_add_u32_e32 v8, s10, v76
	v_ashrrev_i32_e32 v9, 31, v8
	v_lshlrev_b64 v[8:9], s12, v[8:9]
	v_cndmask_b32_e64 v14, v10, v12, s[0:1]
	v_cndmask_b32_e64 v13, v13, v11, s[0:1]
	v_cndmask_b32_e64 v12, v12, v10, s[0:1]
	v_lshl_add_u64 v[8:9], v[2:3], 0, v[8:9]
	global_store_dwordx4 v[8:9], v[12:15], off nt
	v_cndmask_b32_e64 v8, v4, v6, s[0:1]
	v_cndmask_b32_e64 v6, v6, v4, s[0:1]
	v_add_u32_e32 v4, s10, v77
	v_cndmask_b32_e64 v9, v5, v7, s[0:1]
	v_cndmask_b32_e64 v7, v7, v5, s[0:1]
	v_ashrrev_i32_e32 v5, 31, v4
	v_lshlrev_b64 v[4:5], s12, v[4:5]
	v_lshl_add_u64 v[2:3], v[2:3], 0, v[4:5]
	global_store_dwordx4 v[2:3], v[6:9], off nt
	s_cbranch_scc1 .LBB0_218
